# back-edge rotation (7.11) of up K-loop: loop-carried SALU moved from head of first load segment into shadow of last MFMA segment, on v91
# speedup vs baseline: 1.0004x; 1.0004x over previous
; #define PG8_STAGE(bufoff, gbase, voff) do { _Pragma("unroll") for (int _i = 0; _i < 2; ++_i) \
;         __builtin_amdgcn_global_load_lds((const unsigned*)((const char*)(gbase) + (voff)[_i]), (PG8_LAS unsigned*)(lds + (bufoff) + ldsw + _i * 8192), 16, 0, 0); } while (0)
; #define PG8_LDA(dst, b, h) do { _Pragma("unroll") for (int m = 0; m < 4; ++m) _Pragma("unroll") for (int k = 0; k < 2; ++k) dst[m][k] = *(const PG8_LAS bf16x8*)(lds + PG8_SA(b, h) + aoff + m * 2048 + k * 1024); } while (0)
; #define PG8_LDB(dst, b, h) do { _Pragma("unroll") for (int n = 0; n < 2; ++n) _Pragma("unroll") for (int k = 0; k < 2; ++k) dst[n][k] = *(const PG8_LAS bf16x8*)(lds + PG8_SB(b, h) + boff + n * 2048 + k * 1024); } while (0)
; #define PG8_MMA(ai, bj, At, Bt) do { __builtin_amdgcn_s_setprio(1); _Pragma("unroll") for (int m = 0; m < 4; ++m) _Pragma("unroll") for (int n = 0; n < 2; ++n) _Pragma("unroll") for (int k = 0; k < 2; ++k) \
;         acc[ai][bj][m][n] = __builtin_amdgcn_mfma_f32_16x16x32_bf16(Bt[n][k], At[m][k], acc[ai][bj][m][n], 0, 0, 0); __builtin_amdgcn_s_setprio(0); } while (0)
; #define PG8_WAIT_V(n) asm volatile("s_waitcnt vmcnt(" #n ")" ::: "memory")
; template <class Epi, class Sched, bool ALIGN_EPI = false, bool SP2 = false>
; __device__ __forceinline__ void gemm_phase(PG8_LAS unsigned char* lds, const Gemm g, const Sched& S, const Epi& E, const int tid) {
;     ...
;         const bool has_next = S.next(ui + 1, nxt);
;         const char* nA = has_next ? (const char*)g.A + (size_t)nxt.pm * tstep : cA; const char* nB = has_next ? (const char*)g.Bt + (size_t)nxt.pn * tstep : cB;
;         for (int t = 0; t < nt; t += 2) {
;             if constexpr (Epi::MIDK) { if (t == E.midk) E.mid(acc, cur, wr, fr); }
;             const bool last = (t == nt - 2);
;             const char* a1 = cA + (size_t)(t + 1) * kstep;
;             const char* a2 = last ? nA : cA + (size_t)(t + 2) * kstep; const char* b2 = last ? nB : cB + (size_t)(t + 2) * kstep;
;             const char* a3 = a2 + kstep; const char* b3 = b2 + kstep;
;             if (last && has_next) S.a_ready(nxt);
;             if constexpr (SP2) {
;             PG8_LDB(B0, 0, 0); PG8_LDB(B1, 0, 1); PG8_SCHED; PG8_LDA(At, 0, 0); PG8_STAGE(PG8_SA(1, 1), a1 + hstep, voffA);
;             PG8_WAIT_V(8); PG8_WAIT_L(0); PG8_BAR; PG8_MMA(0, 0, At, B0); PG8_MMA(0, 1, At, B1); PG8_BAR; PG8_SCHED;
.LBB0_187:
	s_ashr_i32 s75, s74, 31
	s_lshl_b64 s[36:37], s[74:75], 19
	s_add_u32 s78, s13, s36
	s_addc_u32 s79, s14, s37
	s_and_b64 s[36:37], s[4:5], exec
	s_cselect_b32 s34, s79, s83
	s_cselect_b32 s36, s78, s82
	s_ashr_i32 s77, s76, 31
	s_lshl_b64 s[42:43], s[76:77], 19
	s_add_u32 s80, s17, s42
	s_addc_u32 s81, s18, s43
	s_and_b64 s[42:43], s[4:5], exec
	s_cselect_b32 s37, s81, s85
	s_cselect_b32 s38, s80, s84
	s_add_u32 s40, s84, 0x100
	s_addc_u32 s42, s85, 0
	s_add_u32 s82, s82, 0x40080
	s_addc_u32 s83, s83, 0
	s_mov_b32 s43, -2
	s_waitcnt vmcnt(0)
	s_add_u32 s46, s82, 0xfffc0080
	s_addc_u32 s54, s83, -1
	s_add_i32 s55, 0, 0x10000
	s_cmp_eq_u32 s43, 12
	s_cselect_b32 s87, s34, s54
	s_cselect_b32 s86, s36, s46
	v_add_u32_e32 v149, s55, v146
	s_cselect_b32 s85, s37, s42
	s_cselect_b32 s84, s38, s40
	s_add_i32 s46, 0, 0x14000
	ds_read_b128 v[142:145], v149
	ds_read_b128 v[150:153], v149 offset:1024
	ds_read_b128 v[154:157], v149 offset:2048
	ds_read_b128 v[158:161], v149 offset:3072
	v_add_u32_e32 v149, s46, v146
	ds_read_b128 v[162:165], v149
	ds_read_b128 v[166:169], v149 offset:1024
	ds_read_b128 v[170:173], v149 offset:2048
	ds_read_b128 v[174:177], v149 offset:3072
	v_lshl_add_u64 v[194:195], s[82:83], 0, v[140:141]
	s_add_i32 m0, s20, 0xc000
	ds_read_b128 v[178:181], v148
	ds_read_b128 v[182:185], v148 offset:1024
	ds_read_b128 v[186:189], v148 offset:2048
	ds_read_b128 v[190:193], v148 offset:3072
	ds_read_b128 v[208:211], v148 offset:4096
	ds_read_b128 v[226:229], v148 offset:5120
	ds_read_b128 v[230:233], v148 offset:6144
	ds_read_b128 v[234:237], v148 offset:7168
	global_load_lds_dwordx4 v[194:195], off
	v_lshl_add_u64 v[194:195], s[82:83], 0, v[138:139]
	s_add_i32 m0, s20, 0xe000
	s_nop 0
	global_load_lds_dwordx4 v[194:195], off
	s_waitcnt vmcnt(8)
	s_waitcnt lgkmcnt(0)
	s_barrier
	s_setprio 1
	s_waitcnt lgkmcnt(0)
	v_mfma_f32_16x16x32_bf16 v[126:129], v[142:145], v[178:181], 0
	v_mfma_f32_16x16x32_bf16 v[118:121], v[154:157], v[178:181], 0
	v_mfma_f32_16x16x32_bf16 v[110:113], v[142:145], v[186:189], 0
	v_mfma_f32_16x16x32_bf16 v[102:105], v[154:157], v[186:189], 0
	v_mfma_f32_16x16x32_bf16 v[94:97], v[142:145], v[208:211], 0
	v_mfma_f32_16x16x32_bf16 v[86:89], v[154:157], v[208:211], 0
	v_mfma_f32_16x16x32_bf16 v[78:81], v[142:145], v[230:233], 0
	v_mfma_f32_16x16x32_bf16 v[70:73], v[154:157], v[230:233], 0
	v_mfma_f32_16x16x32_bf16 v[126:129], v[150:153], v[182:185], v[126:129]
	v_mfma_f32_16x16x32_bf16 v[118:121], v[158:161], v[182:185], v[118:121]
	v_mfma_f32_16x16x32_bf16 v[110:113], v[150:153], v[190:193], v[110:113]
	v_mfma_f32_16x16x32_bf16 v[102:105], v[158:161], v[190:193], v[102:105]
	v_mfma_f32_16x16x32_bf16 v[94:97], v[150:153], v[226:229], v[94:97]
	v_mfma_f32_16x16x32_bf16 v[86:89], v[158:161], v[226:229], v[86:89]
	v_mfma_f32_16x16x32_bf16 v[78:81], v[150:153], v[234:237], v[78:81]
	v_mfma_f32_16x16x32_bf16 v[70:73], v[158:161], v[234:237], v[70:73]
	s_setprio 0
	s_setprio 1
	v_mfma_f32_16x16x32_bf16 v[130:133], v[162:165], v[178:181], 0
	v_mfma_f32_16x16x32_bf16 v[122:125], v[170:173], v[178:181], 0
	v_mfma_f32_16x16x32_bf16 v[114:117], v[162:165], v[186:189], 0
	v_mfma_f32_16x16x32_bf16 v[106:109], v[170:173], v[186:189], 0
	v_mfma_f32_16x16x32_bf16 v[98:101], v[162:165], v[208:211], 0
	v_mfma_f32_16x16x32_bf16 v[90:93], v[170:173], v[208:211], 0
	v_mfma_f32_16x16x32_bf16 v[82:85], v[162:165], v[230:233], 0
	v_mfma_f32_16x16x32_bf16 v[74:77], v[170:173], v[230:233], 0
	v_mfma_f32_16x16x32_bf16 v[130:133], v[166:169], v[182:185], v[130:133]
	v_mfma_f32_16x16x32_bf16 v[122:125], v[174:177], v[182:185], v[122:125]
	v_mfma_f32_16x16x32_bf16 v[114:117], v[166:169], v[190:193], v[114:117]
	v_mfma_f32_16x16x32_bf16 v[106:109], v[174:177], v[190:193], v[106:109]
	v_mfma_f32_16x16x32_bf16 v[98:101], v[166:169], v[226:229], v[98:101]
	v_mfma_f32_16x16x32_bf16 v[90:93], v[174:177], v[226:229], v[90:93]
	v_mfma_f32_16x16x32_bf16 v[82:85], v[166:169], v[234:237], v[82:85]
	v_mfma_f32_16x16x32_bf16 v[74:77], v[174:177], v[234:237], v[74:77]
	s_setprio 0
	s_barrier
	s_add_i32 s54, s55, s19
	v_lshl_add_u64 v[194:195], s[84:85], 0, v[0:1]
	s_mov_b32 m0, s54
	ds_read_b128 v[178:181], v148 offset:16384
	ds_read_b128 v[182:185], v148 offset:17408
	ds_read_b128 v[186:189], v148 offset:18432
	ds_read_b128 v[190:193], v148 offset:19456
	ds_read_b128 v[208:211], v148 offset:20480
	ds_read_b128 v[226:229], v148 offset:21504
	ds_read_b128 v[230:233], v148 offset:22528
	ds_read_b128 v[234:237], v148 offset:23552
	global_load_lds_dwordx4 v[194:195], off
	s_add_i32 m0, s54, 0x2000
	s_add_u32 s54, s84, 0x40000
	v_lshl_add_u64 v[238:239], s[84:85], 0, v[2:3]
	s_addc_u32 s55, s85, 0
	s_add_i32 s46, s46, s19
	global_load_lds_dwordx4 v[238:239], off
	v_lshl_add_u64 v[240:241], s[54:55], 0, v[0:1]
	s_mov_b32 m0, s46
	v_lshl_add_u64 v[242:243], s[86:87], 0, v[134:135]
	global_load_lds_dwordx4 v[240:241], off
	v_lshl_add_u64 v[240:241], s[54:55], 0, v[2:3]
	s_add_i32 m0, s46, 0x2000
	s_nop 0
	global_load_lds_dwordx4 v[240:241], off
	v_lshl_add_u64 v[240:241], s[86:87], 0, v[136:137]
	s_mov_b32 m0, s20
	s_nop 0
	global_load_lds_dwordx4 v[240:241], off
	s_mov_b32 m0, s21
	s_nop 0
	global_load_lds_dwordx4 v[242:243], off
	s_waitcnt vmcnt(8)
	s_waitcnt lgkmcnt(0)
	s_barrier
; #define PG8_STAGE(bufoff, gbase, voff) do { _Pragma("unroll") for (int _i = 0; _i < 2; ++_i) \
;         __builtin_amdgcn_global_load_lds((const unsigned*)((const char*)(gbase) + (voff)[_i]), (PG8_LAS unsigned*)(lds + (bufoff) + ldsw + _i * 8192), 16, 0, 0); } while (0)
; #define PG8_LDA(dst, b, h) do { _Pragma("unroll") for (int m = 0; m < 4; ++m) _Pragma("unroll") for (int k = 0; k < 2; ++k) dst[m][k] = *(const PG8_LAS bf16x8*)(lds + PG8_SA(b, h) + aoff + m * 2048 + k * 1024); } while (0)
; #define PG8_LDB(dst, b, h) do { _Pragma("unroll") for (int n = 0; n < 2; ++n) _Pragma("unroll") for (int k = 0; k < 2; ++k) dst[n][k] = *(const PG8_LAS bf16x8*)(lds + PG8_SB(b, h) + boff + n * 2048 + k * 1024); } while (0)
; #define PG8_MMA(ai, bj, At, Bt) do { __builtin_amdgcn_s_setprio(1); _Pragma("unroll") for (int m = 0; m < 4; ++m) _Pragma("unroll") for (int n = 0; n < 2; ++n) _Pragma("unroll") for (int k = 0; k < 2; ++k) \
;         acc[ai][bj][m][n] = __builtin_amdgcn_mfma_f32_16x16x32_bf16(Bt[n][k], At[m][k], acc[ai][bj][m][n], 0, 0, 0); __builtin_amdgcn_s_setprio(0); } while (0)
; #define PG8_WAIT_V(n) asm volatile("s_waitcnt vmcnt(" #n ")" ::: "memory")
; #define PG8_WAIT_L(n) asm volatile("s_waitcnt lgkmcnt(" #n ")" ::: "memory")
; #define PG8_BAR __builtin_amdgcn_s_barrier()
; #define PG8_SCHED __builtin_amdgcn_sched_barrier(0)
; template <class Epi, class Sched, bool ALIGN_EPI = false, bool SP2 = false>
; __device__ __forceinline__ void gemm_phase(PG8_LAS unsigned char* lds, const Gemm g, const Sched& S, const Epi& E, const int tid) {
;     ...
;             PG8_WAIT_V(8); PG8_WAIT_L(0); PG8_BAR; PG8_MMA(0, 0, At, B0); PG8_MMA(0, 1, At, B1); PG8_BAR; PG8_SCHED;
;             PG8_LDA(At, 0, 1); PG8_STAGE(PG8_SB(0, 0), b2, voffB); PG8_STAGE(PG8_SB(0, 1), b2 + hstep, voffB); PG8_STAGE(PG8_SA(0, 0), a2, voffA);
;             PG8_WAIT_V(8); PG8_WAIT_L(0); PG8_BAR; PG8_MMA(1, 0, At, B0); PG8_MMA(1, 1, At, B1); PG8_BAR; PG8_SCHED;
;             PG8_LDB(B0, 1, 0); PG8_LDB(B1, 1, 1); PG8_SCHED; PG8_LDA(At, 1, 0); PG8_STAGE(PG8_SA(0, 1), a2 + hstep, voffA);
;             PG8_WAIT_V(8); PG8_WAIT_L(0); PG8_BAR; PG8_MMA(0, 0, At, B0); PG8_MMA(0, 1, At, B1); PG8_BAR; PG8_SCHED;
	s_setprio 1
	s_waitcnt lgkmcnt(0)
	v_mfma_f32_16x16x32_bf16 v[62:65], v[142:145], v[178:181], 0
	v_mfma_f32_16x16x32_bf16 v[54:57], v[154:157], v[178:181], 0
	v_mfma_f32_16x16x32_bf16 v[46:49], v[142:145], v[186:189], 0
	v_mfma_f32_16x16x32_bf16 v[38:41], v[154:157], v[186:189], 0
	v_mfma_f32_16x16x32_bf16 v[30:33], v[142:145], v[208:211], 0
	v_mfma_f32_16x16x32_bf16 v[22:25], v[154:157], v[208:211], 0
	v_mfma_f32_16x16x32_bf16 v[14:17], v[142:145], v[230:233], 0
	v_mfma_f32_16x16x32_bf16 v[10:13], v[154:157], v[230:233], 0
	v_mfma_f32_16x16x32_bf16 v[62:65], v[150:153], v[182:185], v[62:65]
	v_mfma_f32_16x16x32_bf16 v[54:57], v[158:161], v[182:185], v[54:57]
	v_mfma_f32_16x16x32_bf16 v[46:49], v[150:153], v[190:193], v[46:49]
	v_mfma_f32_16x16x32_bf16 v[38:41], v[158:161], v[190:193], v[38:41]
	v_mfma_f32_16x16x32_bf16 v[30:33], v[150:153], v[226:229], v[30:33]
	v_mfma_f32_16x16x32_bf16 v[22:25], v[158:161], v[226:229], v[22:25]
	v_mfma_f32_16x16x32_bf16 v[14:17], v[150:153], v[234:237], v[14:17]
	v_mfma_f32_16x16x32_bf16 v[10:13], v[158:161], v[234:237], v[10:13]
	s_setprio 0
	s_setprio 1
	v_mfma_f32_16x16x32_bf16 v[66:69], v[162:165], v[178:181], 0
	v_mfma_f32_16x16x32_bf16 v[58:61], v[170:173], v[178:181], 0
	v_mfma_f32_16x16x32_bf16 v[50:53], v[162:165], v[186:189], 0
	v_mfma_f32_16x16x32_bf16 v[42:45], v[170:173], v[186:189], 0
	v_mfma_f32_16x16x32_bf16 v[34:37], v[162:165], v[208:211], 0
	v_mfma_f32_16x16x32_bf16 v[26:29], v[170:173], v[208:211], 0
	v_mfma_f32_16x16x32_bf16 v[18:21], v[162:165], v[230:233], 0
	v_mfma_f32_16x16x32_bf16 v[6:9], v[170:173], v[230:233], 0
	v_mfma_f32_16x16x32_bf16 v[66:69], v[166:169], v[182:185], v[66:69]
	v_mfma_f32_16x16x32_bf16 v[58:61], v[174:177], v[182:185], v[58:61]
	v_mfma_f32_16x16x32_bf16 v[50:53], v[166:169], v[190:193], v[50:53]
	v_mfma_f32_16x16x32_bf16 v[42:45], v[174:177], v[190:193], v[42:45]
	v_mfma_f32_16x16x32_bf16 v[34:37], v[166:169], v[226:229], v[34:37]
	v_mfma_f32_16x16x32_bf16 v[26:29], v[174:177], v[226:229], v[26:29]
	v_mfma_f32_16x16x32_bf16 v[18:21], v[166:169], v[234:237], v[18:21]
	v_mfma_f32_16x16x32_bf16 v[6:9], v[174:177], v[234:237], v[6:9]
	s_setprio 0
	s_barrier
	s_add_i32 s46, 0, 0x18000
	v_add_u32_e32 v149, s46, v146
	s_add_i32 s75, 0, 0x1c000
	ds_read_b128 v[142:145], v149
	ds_read_b128 v[150:153], v149 offset:1024
	ds_read_b128 v[154:157], v149 offset:2048
	ds_read_b128 v[158:161], v149 offset:3072
	v_add_u32_e32 v149, s75, v146
	ds_read_b128 v[162:165], v149
	ds_read_b128 v[166:169], v149 offset:1024
	ds_read_b128 v[170:173], v149 offset:2048
	ds_read_b128 v[174:177], v149 offset:3072
	s_add_u32 s54, s86, 0x40000
	s_addc_u32 s55, s87, 0
	s_mov_b32 m0, s24
	v_lshl_add_u64 v[244:245], s[54:55], 0, v[136:137]
	ds_read_b128 v[178:181], v148 offset:32768
	ds_read_b128 v[182:185], v148 offset:33792
	ds_read_b128 v[186:189], v148 offset:34816
	ds_read_b128 v[190:193], v148 offset:35840
	ds_read_b128 v[208:211], v148 offset:36864
	ds_read_b128 v[226:229], v148 offset:37888
	ds_read_b128 v[230:233], v148 offset:38912
	ds_read_b128 v[234:237], v148 offset:39936
	global_load_lds_dwordx4 v[244:245], off
	v_lshl_add_u64 v[244:245], s[54:55], 0, v[134:135]
	s_mov_b32 m0, s25
	s_nop 0
	global_load_lds_dwordx4 v[244:245], off
	s_waitcnt vmcnt(8)
	s_waitcnt lgkmcnt(0)
	s_barrier
	s_setprio 1
	s_waitcnt lgkmcnt(0)
	v_mfma_f32_16x16x32_bf16 v[126:129], v[142:145], v[178:181], v[126:129]
	v_mfma_f32_16x16x32_bf16 v[118:121], v[154:157], v[178:181], v[118:121]
	v_mfma_f32_16x16x32_bf16 v[110:113], v[142:145], v[186:189], v[110:113]
	v_mfma_f32_16x16x32_bf16 v[102:105], v[154:157], v[186:189], v[102:105]
	v_mfma_f32_16x16x32_bf16 v[94:97], v[142:145], v[208:211], v[94:97]
	v_mfma_f32_16x16x32_bf16 v[86:89], v[154:157], v[208:211], v[86:89]
	v_mfma_f32_16x16x32_bf16 v[78:81], v[142:145], v[230:233], v[78:81]
	v_mfma_f32_16x16x32_bf16 v[70:73], v[154:157], v[230:233], v[70:73]
	v_mfma_f32_16x16x32_bf16 v[126:129], v[150:153], v[182:185], v[126:129]
	v_mfma_f32_16x16x32_bf16 v[118:121], v[158:161], v[182:185], v[118:121]
	v_mfma_f32_16x16x32_bf16 v[110:113], v[150:153], v[190:193], v[110:113]
	v_mfma_f32_16x16x32_bf16 v[102:105], v[158:161], v[190:193], v[102:105]
	v_mfma_f32_16x16x32_bf16 v[94:97], v[150:153], v[226:229], v[94:97]
	v_mfma_f32_16x16x32_bf16 v[86:89], v[158:161], v[226:229], v[86:89]
	v_mfma_f32_16x16x32_bf16 v[78:81], v[150:153], v[234:237], v[78:81]
	v_mfma_f32_16x16x32_bf16 v[70:73], v[158:161], v[234:237], v[70:73]
	s_setprio 0
	s_setprio 1
	v_mfma_f32_16x16x32_bf16 v[130:133], v[162:165], v[178:181], v[130:133]
	v_mfma_f32_16x16x32_bf16 v[122:125], v[170:173], v[178:181], v[122:125]
	v_mfma_f32_16x16x32_bf16 v[114:117], v[162:165], v[186:189], v[114:117]
	v_mfma_f32_16x16x32_bf16 v[106:109], v[170:173], v[186:189], v[106:109]
	v_mfma_f32_16x16x32_bf16 v[98:101], v[162:165], v[208:211], v[98:101]
	v_mfma_f32_16x16x32_bf16 v[90:93], v[170:173], v[208:211], v[90:93]
	v_mfma_f32_16x16x32_bf16 v[82:85], v[162:165], v[230:233], v[82:85]
	v_mfma_f32_16x16x32_bf16 v[74:77], v[170:173], v[230:233], v[74:77]
	v_mfma_f32_16x16x32_bf16 v[130:133], v[166:169], v[182:185], v[130:133]
	v_mfma_f32_16x16x32_bf16 v[122:125], v[174:177], v[182:185], v[122:125]
	v_mfma_f32_16x16x32_bf16 v[114:117], v[166:169], v[190:193], v[114:117]
	v_mfma_f32_16x16x32_bf16 v[106:109], v[174:177], v[190:193], v[106:109]
	v_mfma_f32_16x16x32_bf16 v[98:101], v[166:169], v[226:229], v[98:101]
	v_mfma_f32_16x16x32_bf16 v[90:93], v[174:177], v[226:229], v[90:93]
	v_mfma_f32_16x16x32_bf16 v[82:85], v[166:169], v[234:237], v[82:85]
	v_mfma_f32_16x16x32_bf16 v[74:77], v[174:177], v[234:237], v[74:77]
	s_setprio 0
	s_barrier
; #define PG8_STAGE(bufoff, gbase, voff) do { _Pragma("unroll") for (int _i = 0; _i < 2; ++_i) \
;         __builtin_amdgcn_global_load_lds((const unsigned*)((const char*)(gbase) + (voff)[_i]), (PG8_LAS unsigned*)(lds + (bufoff) + ldsw + _i * 8192), 16, 0, 0); } while (0)
; #define PG8_LDA(dst, b, h) do { _Pragma("unroll") for (int m = 0; m < 4; ++m) _Pragma("unroll") for (int k = 0; k < 2; ++k) dst[m][k] = *(const PG8_LAS bf16x8*)(lds + PG8_SA(b, h) + aoff + m * 2048 + k * 1024); } while (0)
; #define PG8_MMA(ai, bj, At, Bt) do { __builtin_amdgcn_s_setprio(1); _Pragma("unroll") for (int m = 0; m < 4; ++m) _Pragma("unroll") for (int n = 0; n < 2; ++n) _Pragma("unroll") for (int k = 0; k < 2; ++k) \
;         acc[ai][bj][m][n] = __builtin_amdgcn_mfma_f32_16x16x32_bf16(Bt[n][k], At[m][k], acc[ai][bj][m][n], 0, 0, 0); __builtin_amdgcn_s_setprio(0); } while (0)
; #define PG8_WAIT_V(n) asm volatile("s_waitcnt vmcnt(" #n ")" ::: "memory")
; #define PG8_WAIT_L(n) asm volatile("s_waitcnt lgkmcnt(" #n ")" ::: "memory")
; #define PG8_BAR __builtin_amdgcn_s_barrier()
; #define PG8_SCHED __builtin_amdgcn_sched_barrier(0)
; template <class Epi, class Sched, bool ALIGN_EPI = false, bool SP2 = false>
; __device__ __forceinline__ void gemm_phase(PG8_LAS unsigned char* lds, const Gemm g, const Sched& S, const Epi& E, const int tid) {
;     ...
;         for (int t = 0; t < nt; t += 2) {
;             if constexpr (Epi::MIDK) { if (t == E.midk) E.mid(acc, cur, wr, fr); }
;             const bool last = (t == nt - 2);
;             const char* a1 = cA + (size_t)(t + 1) * kstep;
;             const char* a2 = last ? nA : cA + (size_t)(t + 2) * kstep; const char* b2 = last ? nB : cB + (size_t)(t + 2) * kstep;
;             const char* a3 = a2 + kstep; const char* b3 = b2 + kstep;
;             if (last && has_next) S.a_ready(nxt);
;     ...
;             PG8_WAIT_V(8); PG8_WAIT_L(0); PG8_BAR; PG8_MMA(0, 0, At, B0); PG8_MMA(0, 1, At, B1); PG8_BAR; PG8_SCHED;
;             PG8_LDA(At, 1, 1); PG8_STAGE(PG8_SB(1, 0), b3, voffB); PG8_STAGE(PG8_SB(1, 1), b3 + hstep, voffB); PG8_STAGE(PG8_SA(1, 0), a3, voffA);
;             PG8_WAIT_V(8); PG8_WAIT_L(0); PG8_BAR; PG8_MMA(1, 0, At, B0); PG8_MMA(1, 1, At, B1); PG8_BAR; PG8_SCHED;
	s_add_i32 s46, s46, s19
	v_lshl_add_u64 v[194:195], v[194:195], 0, s[50:51]
	s_mov_b32 m0, s46
	ds_read_b128 v[178:181], v148 offset:49152
	ds_read_b128 v[182:185], v148 offset:50176
	ds_read_b128 v[186:189], v148 offset:51200
	ds_read_b128 v[190:193], v148 offset:52224
	ds_read_b128 v[208:211], v148 offset:53248
	ds_read_b128 v[226:229], v148 offset:54272
	ds_read_b128 v[230:233], v148 offset:55296
	ds_read_b128 v[234:237], v148 offset:56320
	global_load_lds_dwordx4 v[194:195], off
	s_add_i32 m0, s46, 0x2000
	s_add_u32 s54, s84, 0x40080
	v_lshl_add_u64 v[194:195], v[238:239], 0, s[50:51]
	s_addc_u32 s55, s85, 0
	s_add_i32 s46, s75, s19
	global_load_lds_dwordx4 v[194:195], off
	v_lshl_add_u64 v[194:195], s[54:55], 0, v[0:1]
	s_mov_b32 m0, s46
	s_nop 0
	global_load_lds_dwordx4 v[194:195], off
	v_lshl_add_u64 v[194:195], s[54:55], 0, v[2:3]
	s_add_i32 m0, s46, 0x2000
	s_nop 0
	global_load_lds_dwordx4 v[194:195], off
	v_lshl_add_u64 v[194:195], v[240:241], 0, s[50:51]
	s_mov_b32 m0, s28
	s_nop 0
	global_load_lds_dwordx4 v[194:195], off
	v_lshl_add_u64 v[194:195], v[242:243], 0, s[50:51]
	s_mov_b32 m0, s30
	s_nop 0
	global_load_lds_dwordx4 v[194:195], off
	s_waitcnt vmcnt(8)
	s_waitcnt lgkmcnt(0)
	s_barrier
	s_setprio 1
	s_waitcnt lgkmcnt(0)
	v_mfma_f32_16x16x32_bf16 v[62:65], v[142:145], v[178:181], v[62:65]
	v_mfma_f32_16x16x32_bf16 v[54:57], v[154:157], v[178:181], v[54:57]
	s_add_i32 s43, s43, 2
	v_mfma_f32_16x16x32_bf16 v[46:49], v[142:145], v[186:189], v[46:49]
	s_add_u32 s40, s40, 0x100
	v_mfma_f32_16x16x32_bf16 v[38:41], v[154:157], v[186:189], v[38:41]
	s_addc_u32 s42, s42, 0
	v_mfma_f32_16x16x32_bf16 v[30:33], v[142:145], v[208:211], v[30:33]
	s_add_u32 s82, s82, 0x100
	v_mfma_f32_16x16x32_bf16 v[22:25], v[154:157], v[208:211], v[22:25]
	s_addc_u32 s83, s83, 0
	v_mfma_f32_16x16x32_bf16 v[14:17], v[142:145], v[230:233], v[14:17]
	s_add_u32 s46, s82, 0xfffc0080
	v_mfma_f32_16x16x32_bf16 v[10:13], v[154:157], v[230:233], v[10:13]
	s_addc_u32 s54, s83, -1
	v_mfma_f32_16x16x32_bf16 v[62:65], v[150:153], v[182:185], v[62:65]
	s_add_i32 s55, 0, 0x10000
	v_mfma_f32_16x16x32_bf16 v[54:57], v[158:161], v[182:185], v[54:57]
	s_cmp_eq_u32 s43, 12
	v_mfma_f32_16x16x32_bf16 v[46:49], v[150:153], v[190:193], v[46:49]
	s_cselect_b32 s87, s34, s54
	v_mfma_f32_16x16x32_bf16 v[38:41], v[158:161], v[190:193], v[38:41]
	s_cselect_b32 s86, s36, s46
	v_mfma_f32_16x16x32_bf16 v[30:33], v[150:153], v[226:229], v[30:33]
	v_add_u32_e32 v149, s55, v146
	v_mfma_f32_16x16x32_bf16 v[22:25], v[158:161], v[226:229], v[22:25]
	s_cselect_b32 s85, s37, s42
	v_mfma_f32_16x16x32_bf16 v[14:17], v[150:153], v[234:237], v[14:17]
	s_cselect_b32 s84, s38, s40
	v_mfma_f32_16x16x32_bf16 v[10:13], v[158:161], v[234:237], v[10:13]
	s_add_i32 s46, 0, 0x14000
	s_setprio 0
	s_setprio 1
	v_mfma_f32_16x16x32_bf16 v[66:69], v[162:165], v[178:181], v[66:69]
	v_mfma_f32_16x16x32_bf16 v[58:61], v[170:173], v[178:181], v[58:61]
	v_mfma_f32_16x16x32_bf16 v[50:53], v[162:165], v[186:189], v[50:53]
	v_mfma_f32_16x16x32_bf16 v[42:45], v[170:173], v[186:189], v[42:45]
	v_mfma_f32_16x16x32_bf16 v[34:37], v[162:165], v[208:211], v[34:37]
	v_mfma_f32_16x16x32_bf16 v[26:29], v[170:173], v[208:211], v[26:29]
	v_mfma_f32_16x16x32_bf16 v[18:21], v[162:165], v[230:233], v[18:21]
	v_mfma_f32_16x16x32_bf16 v[6:9], v[170:173], v[230:233], v[6:9]
	v_mfma_f32_16x16x32_bf16 v[66:69], v[166:169], v[182:185], v[66:69]
	v_mfma_f32_16x16x32_bf16 v[58:61], v[174:177], v[182:185], v[58:61]
	v_mfma_f32_16x16x32_bf16 v[50:53], v[166:169], v[190:193], v[50:53]
	v_mfma_f32_16x16x32_bf16 v[42:45], v[174:177], v[190:193], v[42:45]
	v_mfma_f32_16x16x32_bf16 v[34:37], v[166:169], v[226:229], v[34:37]
	v_mfma_f32_16x16x32_bf16 v[26:29], v[174:177], v[226:229], v[26:29]
	v_mfma_f32_16x16x32_bf16 v[18:21], v[166:169], v[234:237], v[18:21]
	v_mfma_f32_16x16x32_bf16 v[6:9], v[174:177], v[234:237], v[6:9]
	s_setprio 0
	s_barrier
	s_cmp_gt_u32 s43, 13
.LBB0_188:
	ds_read_b128 v[142:145], v149
	ds_read_b128 v[150:153], v149 offset:1024
	ds_read_b128 v[154:157], v149 offset:2048
	ds_read_b128 v[158:161], v149 offset:3072
	v_add_u32_e32 v149, s46, v146
	ds_read_b128 v[162:165], v149
	ds_read_b128 v[166:169], v149 offset:1024
	ds_read_b128 v[170:173], v149 offset:2048
	ds_read_b128 v[174:177], v149 offset:3072
	v_lshl_add_u64 v[194:195], s[82:83], 0, v[140:141]
	s_add_i32 m0, s20, 0xc000
	ds_read_b128 v[178:181], v148
	ds_read_b128 v[182:185], v148 offset:1024
	ds_read_b128 v[186:189], v148 offset:2048
	ds_read_b128 v[190:193], v148 offset:3072
	ds_read_b128 v[208:211], v148 offset:4096
	ds_read_b128 v[226:229], v148 offset:5120
	ds_read_b128 v[230:233], v148 offset:6144
	ds_read_b128 v[234:237], v148 offset:7168
	global_load_lds_dwordx4 v[194:195], off
	v_lshl_add_u64 v[194:195], s[82:83], 0, v[138:139]
	s_add_i32 m0, s20, 0xe000
	s_nop 0
	global_load_lds_dwordx4 v[194:195], off
	s_waitcnt vmcnt(8)
	s_waitcnt lgkmcnt(0)
	s_barrier
; #define PG8_STAGE(bufoff, gbase, voff) do { _Pragma("unroll") for (int _i = 0; _i < 2; ++_i) \
;         __builtin_amdgcn_global_load_lds((const unsigned*)((const char*)(gbase) + (voff)[_i]), (PG8_LAS unsigned*)(lds + (bufoff) + ldsw + _i * 8192), 16, 0, 0); } while (0)
; #define PG8_LDA(dst, b, h) do { _Pragma("unroll") for (int m = 0; m < 4; ++m) _Pragma("unroll") for (int k = 0; k < 2; ++k) dst[m][k] = *(const PG8_LAS bf16x8*)(lds + PG8_SA(b, h) + aoff + m * 2048 + k * 1024); } while (0)
; #define PG8_LDB(dst, b, h) do { _Pragma("unroll") for (int n = 0; n < 2; ++n) _Pragma("unroll") for (int k = 0; k < 2; ++k) dst[n][k] = *(const PG8_LAS bf16x8*)(lds + PG8_SB(b, h) + boff + n * 2048 + k * 1024); } while (0)
; #define PG8_MMA(ai, bj, At, Bt) do { __builtin_amdgcn_s_setprio(1); _Pragma("unroll") for (int m = 0; m < 4; ++m) _Pragma("unroll") for (int n = 0; n < 2; ++n) _Pragma("unroll") for (int k = 0; k < 2; ++k) \
;         acc[ai][bj][m][n] = __builtin_amdgcn_mfma_f32_16x16x32_bf16(Bt[n][k], At[m][k], acc[ai][bj][m][n], 0, 0, 0); __builtin_amdgcn_s_setprio(0); } while (0)
; #define PG8_WAIT_V(n) asm volatile("s_waitcnt vmcnt(" #n ")" ::: "memory")
; #define PG8_WAIT_L(n) asm volatile("s_waitcnt lgkmcnt(" #n ")" ::: "memory")
; #define PG8_BAR __builtin_amdgcn_s_barrier()
; #define PG8_SCHED __builtin_amdgcn_sched_barrier(0)
; template <class Epi, class Sched, bool ALIGN_EPI = false, bool SP2 = false>
; __device__ __forceinline__ void gemm_phase(PG8_LAS unsigned char* lds, const Gemm g, const Sched& S, const Epi& E, const int tid) {
;     ...
;             if constexpr (SP2) {
;             PG8_LDB(B0, 0, 0); PG8_LDB(B1, 0, 1); PG8_SCHED; PG8_LDA(At, 0, 0); PG8_STAGE(PG8_SA(1, 1), a1 + hstep, voffA);
;             PG8_WAIT_V(8); PG8_WAIT_L(0); PG8_BAR; PG8_MMA(0, 0, At, B0); PG8_MMA(0, 1, At, B1); PG8_BAR; PG8_SCHED;
;             PG8_LDA(At, 0, 1); PG8_STAGE(PG8_SB(0, 0), b2, voffB); PG8_STAGE(PG8_SB(0, 1), b2 + hstep, voffB); PG8_STAGE(PG8_SA(0, 0), a2, voffA);
;             PG8_WAIT_V(8); PG8_WAIT_L(0); PG8_BAR; PG8_MMA(1, 0, At, B0); PG8_MMA(1, 1, At, B1); PG8_BAR; PG8_SCHED;
;             PG8_LDB(B0, 1, 0); PG8_LDB(B1, 1, 1); PG8_SCHED; PG8_LDA(At, 1, 0); PG8_STAGE(PG8_SA(0, 1), a2 + hstep, voffA);
	s_setprio 1
	s_waitcnt lgkmcnt(0)
	v_mfma_f32_16x16x32_bf16 v[126:129], v[142:145], v[178:181], v[126:129]
	v_mfma_f32_16x16x32_bf16 v[118:121], v[154:157], v[178:181], v[118:121]
	v_mfma_f32_16x16x32_bf16 v[110:113], v[142:145], v[186:189], v[110:113]
	v_mfma_f32_16x16x32_bf16 v[102:105], v[154:157], v[186:189], v[102:105]
	v_mfma_f32_16x16x32_bf16 v[94:97], v[142:145], v[208:211], v[94:97]
	v_mfma_f32_16x16x32_bf16 v[86:89], v[154:157], v[208:211], v[86:89]
	v_mfma_f32_16x16x32_bf16 v[78:81], v[142:145], v[230:233], v[78:81]
	v_mfma_f32_16x16x32_bf16 v[70:73], v[154:157], v[230:233], v[70:73]
	v_mfma_f32_16x16x32_bf16 v[126:129], v[150:153], v[182:185], v[126:129]
	v_mfma_f32_16x16x32_bf16 v[118:121], v[158:161], v[182:185], v[118:121]
	v_mfma_f32_16x16x32_bf16 v[110:113], v[150:153], v[190:193], v[110:113]
	v_mfma_f32_16x16x32_bf16 v[102:105], v[158:161], v[190:193], v[102:105]
	v_mfma_f32_16x16x32_bf16 v[94:97], v[150:153], v[226:229], v[94:97]
	v_mfma_f32_16x16x32_bf16 v[86:89], v[158:161], v[226:229], v[86:89]
	v_mfma_f32_16x16x32_bf16 v[78:81], v[150:153], v[234:237], v[78:81]
	v_mfma_f32_16x16x32_bf16 v[70:73], v[158:161], v[234:237], v[70:73]
	s_setprio 0
	s_setprio 1
	v_mfma_f32_16x16x32_bf16 v[130:133], v[162:165], v[178:181], v[130:133]
	v_mfma_f32_16x16x32_bf16 v[122:125], v[170:173], v[178:181], v[122:125]
	v_mfma_f32_16x16x32_bf16 v[114:117], v[162:165], v[186:189], v[114:117]
	v_mfma_f32_16x16x32_bf16 v[106:109], v[170:173], v[186:189], v[106:109]
	v_mfma_f32_16x16x32_bf16 v[98:101], v[162:165], v[208:211], v[98:101]
	v_mfma_f32_16x16x32_bf16 v[90:93], v[170:173], v[208:211], v[90:93]
	v_mfma_f32_16x16x32_bf16 v[82:85], v[162:165], v[230:233], v[82:85]
	v_mfma_f32_16x16x32_bf16 v[74:77], v[170:173], v[230:233], v[74:77]
	v_mfma_f32_16x16x32_bf16 v[130:133], v[166:169], v[182:185], v[130:133]
	v_mfma_f32_16x16x32_bf16 v[122:125], v[174:177], v[182:185], v[122:125]
	v_mfma_f32_16x16x32_bf16 v[114:117], v[166:169], v[190:193], v[114:117]
	v_mfma_f32_16x16x32_bf16 v[106:109], v[174:177], v[190:193], v[106:109]
	v_mfma_f32_16x16x32_bf16 v[98:101], v[166:169], v[226:229], v[98:101]
	v_mfma_f32_16x16x32_bf16 v[90:93], v[174:177], v[226:229], v[90:93]
	v_mfma_f32_16x16x32_bf16 v[82:85], v[166:169], v[234:237], v[82:85]
	v_mfma_f32_16x16x32_bf16 v[74:77], v[174:177], v[234:237], v[74:77]
	s_setprio 0
	s_barrier
	s_add_i32 s54, s55, s19
	v_lshl_add_u64 v[194:195], s[84:85], 0, v[0:1]
	s_mov_b32 m0, s54
	ds_read_b128 v[178:181], v148 offset:16384
	ds_read_b128 v[182:185], v148 offset:17408
	ds_read_b128 v[186:189], v148 offset:18432
	ds_read_b128 v[190:193], v148 offset:19456
	ds_read_b128 v[208:211], v148 offset:20480
	ds_read_b128 v[226:229], v148 offset:21504
	ds_read_b128 v[230:233], v148 offset:22528
	ds_read_b128 v[234:237], v148 offset:23552
	global_load_lds_dwordx4 v[194:195], off
	s_add_i32 m0, s54, 0x2000
	s_add_u32 s54, s84, 0x40000
	v_lshl_add_u64 v[238:239], s[84:85], 0, v[2:3]
	s_addc_u32 s55, s85, 0
	s_add_i32 s46, s46, s19
	global_load_lds_dwordx4 v[238:239], off
	v_lshl_add_u64 v[240:241], s[54:55], 0, v[0:1]
	s_mov_b32 m0, s46
	v_lshl_add_u64 v[242:243], s[86:87], 0, v[134:135]
	global_load_lds_dwordx4 v[240:241], off
	v_lshl_add_u64 v[240:241], s[54:55], 0, v[2:3]
	s_add_i32 m0, s46, 0x2000
	s_nop 0
	global_load_lds_dwordx4 v[240:241], off
	v_lshl_add_u64 v[240:241], s[86:87], 0, v[136:137]
	s_mov_b32 m0, s20
	s_nop 0
	global_load_lds_dwordx4 v[240:241], off
	s_mov_b32 m0, s21
	s_nop 0
	global_load_lds_dwordx4 v[242:243], off
	s_waitcnt vmcnt(8)
	s_waitcnt lgkmcnt(0)
	s_barrier
	s_setprio 1
	s_waitcnt lgkmcnt(0)
	v_mfma_f32_16x16x32_bf16 v[62:65], v[142:145], v[178:181], v[62:65]
	v_mfma_f32_16x16x32_bf16 v[54:57], v[154:157], v[178:181], v[54:57]
	v_mfma_f32_16x16x32_bf16 v[46:49], v[142:145], v[186:189], v[46:49]
	v_mfma_f32_16x16x32_bf16 v[38:41], v[154:157], v[186:189], v[38:41]
	v_mfma_f32_16x16x32_bf16 v[30:33], v[142:145], v[208:211], v[30:33]
	v_mfma_f32_16x16x32_bf16 v[22:25], v[154:157], v[208:211], v[22:25]
	v_mfma_f32_16x16x32_bf16 v[14:17], v[142:145], v[230:233], v[14:17]
	v_mfma_f32_16x16x32_bf16 v[10:13], v[154:157], v[230:233], v[10:13]
	v_mfma_f32_16x16x32_bf16 v[62:65], v[150:153], v[182:185], v[62:65]
	v_mfma_f32_16x16x32_bf16 v[54:57], v[158:161], v[182:185], v[54:57]
	v_mfma_f32_16x16x32_bf16 v[46:49], v[150:153], v[190:193], v[46:49]
	v_mfma_f32_16x16x32_bf16 v[38:41], v[158:161], v[190:193], v[38:41]
	v_mfma_f32_16x16x32_bf16 v[30:33], v[150:153], v[226:229], v[30:33]
	v_mfma_f32_16x16x32_bf16 v[22:25], v[158:161], v[226:229], v[22:25]
	v_mfma_f32_16x16x32_bf16 v[14:17], v[150:153], v[234:237], v[14:17]
	v_mfma_f32_16x16x32_bf16 v[10:13], v[158:161], v[234:237], v[10:13]
	s_setprio 0
	s_setprio 1
	v_mfma_f32_16x16x32_bf16 v[66:69], v[162:165], v[178:181], v[66:69]
	v_mfma_f32_16x16x32_bf16 v[58:61], v[170:173], v[178:181], v[58:61]
	v_mfma_f32_16x16x32_bf16 v[50:53], v[162:165], v[186:189], v[50:53]
	v_mfma_f32_16x16x32_bf16 v[42:45], v[170:173], v[186:189], v[42:45]
	v_mfma_f32_16x16x32_bf16 v[34:37], v[162:165], v[208:211], v[34:37]
	v_mfma_f32_16x16x32_bf16 v[26:29], v[170:173], v[208:211], v[26:29]
	v_mfma_f32_16x16x32_bf16 v[18:21], v[162:165], v[230:233], v[18:21]
	v_mfma_f32_16x16x32_bf16 v[6:9], v[170:173], v[230:233], v[6:9]
	v_mfma_f32_16x16x32_bf16 v[66:69], v[166:169], v[182:185], v[66:69]
	v_mfma_f32_16x16x32_bf16 v[58:61], v[174:177], v[182:185], v[58:61]
	v_mfma_f32_16x16x32_bf16 v[50:53], v[166:169], v[190:193], v[50:53]
	v_mfma_f32_16x16x32_bf16 v[42:45], v[174:177], v[190:193], v[42:45]
	v_mfma_f32_16x16x32_bf16 v[34:37], v[166:169], v[226:229], v[34:37]
	v_mfma_f32_16x16x32_bf16 v[26:29], v[174:177], v[226:229], v[26:29]
	v_mfma_f32_16x16x32_bf16 v[18:21], v[166:169], v[234:237], v[18:21]
	v_mfma_f32_16x16x32_bf16 v[6:9], v[174:177], v[234:237], v[6:9]
	s_setprio 0
	s_barrier
; #define PG8_STAGE(bufoff, gbase, voff) do { _Pragma("unroll") for (int _i = 0; _i < 2; ++_i) \
;         __builtin_amdgcn_global_load_lds((const unsigned*)((const char*)(gbase) + (voff)[_i]), (PG8_LAS unsigned*)(lds + (bufoff) + ldsw + _i * 8192), 16, 0, 0); } while (0)
; #define PG8_LDA(dst, b, h) do { _Pragma("unroll") for (int m = 0; m < 4; ++m) _Pragma("unroll") for (int k = 0; k < 2; ++k) dst[m][k] = *(const PG8_LAS bf16x8*)(lds + PG8_SA(b, h) + aoff + m * 2048 + k * 1024); } while (0)
; #define PG8_LDB(dst, b, h) do { _Pragma("unroll") for (int n = 0; n < 2; ++n) _Pragma("unroll") for (int k = 0; k < 2; ++k) dst[n][k] = *(const PG8_LAS bf16x8*)(lds + PG8_SB(b, h) + boff + n * 2048 + k * 1024); } while (0)
; #define PG8_MMA(ai, bj, At, Bt) do { __builtin_amdgcn_s_setprio(1); _Pragma("unroll") for (int m = 0; m < 4; ++m) _Pragma("unroll") for (int n = 0; n < 2; ++n) _Pragma("unroll") for (int k = 0; k < 2; ++k) \
;         acc[ai][bj][m][n] = __builtin_amdgcn_mfma_f32_16x16x32_bf16(Bt[n][k], At[m][k], acc[ai][bj][m][n], 0, 0, 0); __builtin_amdgcn_s_setprio(0); } while (0)
; #define PG8_WAIT_V(n) asm volatile("s_waitcnt vmcnt(" #n ")" ::: "memory")
; #define PG8_WAIT_L(n) asm volatile("s_waitcnt lgkmcnt(" #n ")" ::: "memory")
; #define PG8_BAR __builtin_amdgcn_s_barrier()
; #define PG8_SCHED __builtin_amdgcn_sched_barrier(0)
; template <class Epi, class Sched, bool ALIGN_EPI = false, bool SP2 = false>
; __device__ __forceinline__ void gemm_phase(PG8_LAS unsigned char* lds, const Gemm g, const Sched& S, const Epi& E, const int tid) {
;     ...
;             PG8_LDB(B0, 1, 0); PG8_LDB(B1, 1, 1); PG8_SCHED; PG8_LDA(At, 1, 0); PG8_STAGE(PG8_SA(0, 1), a2 + hstep, voffA);
;             PG8_WAIT_V(8); PG8_WAIT_L(0); PG8_BAR; PG8_MMA(0, 0, At, B0); PG8_MMA(0, 1, At, B1); PG8_BAR; PG8_SCHED;
	s_add_i32 s46, 0, 0x18000
	v_add_u32_e32 v149, s46, v146
	s_add_i32 s75, 0, 0x1c000
	ds_read_b128 v[142:145], v149
	ds_read_b128 v[150:153], v149 offset:1024
	ds_read_b128 v[154:157], v149 offset:2048
	ds_read_b128 v[158:161], v149 offset:3072
	v_add_u32_e32 v149, s75, v146
	ds_read_b128 v[162:165], v149
	ds_read_b128 v[166:169], v149 offset:1024
	ds_read_b128 v[170:173], v149 offset:2048
	ds_read_b128 v[174:177], v149 offset:3072
	s_add_u32 s54, s86, 0x40000
	s_addc_u32 s55, s87, 0
	s_mov_b32 m0, s24
	v_lshl_add_u64 v[244:245], s[54:55], 0, v[136:137]
	ds_read_b128 v[178:181], v148 offset:32768
	ds_read_b128 v[182:185], v148 offset:33792
	ds_read_b128 v[186:189], v148 offset:34816
	ds_read_b128 v[190:193], v148 offset:35840
	ds_read_b128 v[208:211], v148 offset:36864
	ds_read_b128 v[226:229], v148 offset:37888
	ds_read_b128 v[230:233], v148 offset:38912
	ds_read_b128 v[234:237], v148 offset:39936
	global_load_lds_dwordx4 v[244:245], off
	v_lshl_add_u64 v[244:245], s[54:55], 0, v[134:135]
	s_mov_b32 m0, s25
	s_nop 0
	global_load_lds_dwordx4 v[244:245], off
	s_waitcnt vmcnt(8)
	s_waitcnt lgkmcnt(0)
	s_barrier
	s_setprio 1
	s_waitcnt lgkmcnt(0)
	v_mfma_f32_16x16x32_bf16 v[126:129], v[142:145], v[178:181], v[126:129]
	v_mfma_f32_16x16x32_bf16 v[118:121], v[154:157], v[178:181], v[118:121]
	v_mfma_f32_16x16x32_bf16 v[110:113], v[142:145], v[186:189], v[110:113]
	v_mfma_f32_16x16x32_bf16 v[102:105], v[154:157], v[186:189], v[102:105]
	v_mfma_f32_16x16x32_bf16 v[94:97], v[142:145], v[208:211], v[94:97]
	v_mfma_f32_16x16x32_bf16 v[86:89], v[154:157], v[208:211], v[86:89]
	v_mfma_f32_16x16x32_bf16 v[78:81], v[142:145], v[230:233], v[78:81]
	v_mfma_f32_16x16x32_bf16 v[70:73], v[154:157], v[230:233], v[70:73]
	v_mfma_f32_16x16x32_bf16 v[126:129], v[150:153], v[182:185], v[126:129]
	v_mfma_f32_16x16x32_bf16 v[118:121], v[158:161], v[182:185], v[118:121]
	v_mfma_f32_16x16x32_bf16 v[110:113], v[150:153], v[190:193], v[110:113]
	v_mfma_f32_16x16x32_bf16 v[102:105], v[158:161], v[190:193], v[102:105]
	v_mfma_f32_16x16x32_bf16 v[94:97], v[150:153], v[226:229], v[94:97]
	v_mfma_f32_16x16x32_bf16 v[86:89], v[158:161], v[226:229], v[86:89]
	v_mfma_f32_16x16x32_bf16 v[78:81], v[150:153], v[234:237], v[78:81]
	v_mfma_f32_16x16x32_bf16 v[70:73], v[158:161], v[234:237], v[70:73]
	s_setprio 0
	s_setprio 1
	v_mfma_f32_16x16x32_bf16 v[130:133], v[162:165], v[178:181], v[130:133]
	v_mfma_f32_16x16x32_bf16 v[122:125], v[170:173], v[178:181], v[122:125]
	v_mfma_f32_16x16x32_bf16 v[114:117], v[162:165], v[186:189], v[114:117]
	v_mfma_f32_16x16x32_bf16 v[106:109], v[170:173], v[186:189], v[106:109]
	v_mfma_f32_16x16x32_bf16 v[98:101], v[162:165], v[208:211], v[98:101]
	v_mfma_f32_16x16x32_bf16 v[90:93], v[170:173], v[208:211], v[90:93]
	v_mfma_f32_16x16x32_bf16 v[82:85], v[162:165], v[230:233], v[82:85]
	v_mfma_f32_16x16x32_bf16 v[74:77], v[170:173], v[230:233], v[74:77]
	v_mfma_f32_16x16x32_bf16 v[130:133], v[166:169], v[182:185], v[130:133]
	v_mfma_f32_16x16x32_bf16 v[122:125], v[174:177], v[182:185], v[122:125]
	v_mfma_f32_16x16x32_bf16 v[114:117], v[166:169], v[190:193], v[114:117]
	v_mfma_f32_16x16x32_bf16 v[106:109], v[174:177], v[190:193], v[106:109]
	v_mfma_f32_16x16x32_bf16 v[98:101], v[166:169], v[226:229], v[98:101]
	v_mfma_f32_16x16x32_bf16 v[90:93], v[174:177], v[226:229], v[90:93]
	v_mfma_f32_16x16x32_bf16 v[82:85], v[166:169], v[234:237], v[82:85]
	v_mfma_f32_16x16x32_bf16 v[74:77], v[174:177], v[234:237], v[74:77]
	s_setprio 0
	s_barrier
; #define PG8_STAGE(bufoff, gbase, voff) do { _Pragma("unroll") for (int _i = 0; _i < 2; ++_i) \
;         __builtin_amdgcn_global_load_lds((const unsigned*)((const char*)(gbase) + (voff)[_i]), (PG8_LAS unsigned*)(lds + (bufoff) + ldsw + _i * 8192), 16, 0, 0); } while (0)
; #define PG8_LDA(dst, b, h) do { _Pragma("unroll") for (int m = 0; m < 4; ++m) _Pragma("unroll") for (int k = 0; k < 2; ++k) dst[m][k] = *(const PG8_LAS bf16x8*)(lds + PG8_SA(b, h) + aoff + m * 2048 + k * 1024); } while (0)
; #define PG8_MMA(ai, bj, At, Bt) do { __builtin_amdgcn_s_setprio(1); _Pragma("unroll") for (int m = 0; m < 4; ++m) _Pragma("unroll") for (int n = 0; n < 2; ++n) _Pragma("unroll") for (int k = 0; k < 2; ++k) \
;         acc[ai][bj][m][n] = __builtin_amdgcn_mfma_f32_16x16x32_bf16(Bt[n][k], At[m][k], acc[ai][bj][m][n], 0, 0, 0); __builtin_amdgcn_s_setprio(0); } while (0)
; #define PG8_WAIT_V(n) asm volatile("s_waitcnt vmcnt(" #n ")" ::: "memory")
; #define PG8_WAIT_L(n) asm volatile("s_waitcnt lgkmcnt(" #n ")" ::: "memory")
; #define PG8_BAR __builtin_amdgcn_s_barrier()
; #define PG8_SCHED __builtin_amdgcn_sched_barrier(0)
; template <class Epi, class Sched, bool ALIGN_EPI = false, bool SP2 = false>
; __device__ __forceinline__ void gemm_phase(PG8_LAS unsigned char* lds, const Gemm g, const Sched& S, const Epi& E, const int tid) {
;     ...
;         for (int t = 0; t < nt; t += 2) {
;             if constexpr (Epi::MIDK) { if (t == E.midk) E.mid(acc, cur, wr, fr); }
;             const bool last = (t == nt - 2);
;             const char* a1 = cA + (size_t)(t + 1) * kstep;
;             const char* a2 = last ? nA : cA + (size_t)(t + 2) * kstep; const char* b2 = last ? nB : cB + (size_t)(t + 2) * kstep;
;             const char* a3 = a2 + kstep; const char* b3 = b2 + kstep;
;             if (last && has_next) S.a_ready(nxt);
;     ...
;             PG8_LDA(At, 1, 1); PG8_STAGE(PG8_SB(1, 0), b3, voffB); PG8_STAGE(PG8_SB(1, 1), b3 + hstep, voffB); PG8_STAGE(PG8_SA(1, 0), a3, voffA);
;             PG8_WAIT_V(8); PG8_WAIT_L(0); PG8_BAR; PG8_MMA(1, 0, At, B0); PG8_MMA(1, 1, At, B1); PG8_BAR; PG8_SCHED;
	s_add_i32 s46, s46, s19
	v_lshl_add_u64 v[194:195], v[194:195], 0, s[50:51]
	s_mov_b32 m0, s46
	ds_read_b128 v[178:181], v148 offset:49152
	ds_read_b128 v[182:185], v148 offset:50176
	ds_read_b128 v[186:189], v148 offset:51200
	ds_read_b128 v[190:193], v148 offset:52224
	ds_read_b128 v[208:211], v148 offset:53248
	ds_read_b128 v[226:229], v148 offset:54272
	ds_read_b128 v[230:233], v148 offset:55296
	ds_read_b128 v[234:237], v148 offset:56320
	global_load_lds_dwordx4 v[194:195], off
	s_add_i32 m0, s46, 0x2000
	s_add_u32 s54, s84, 0x40080
	v_lshl_add_u64 v[194:195], v[238:239], 0, s[50:51]
	s_addc_u32 s55, s85, 0
	s_add_i32 s46, s75, s19
	global_load_lds_dwordx4 v[194:195], off
	v_lshl_add_u64 v[194:195], s[54:55], 0, v[0:1]
	s_mov_b32 m0, s46
	s_nop 0
	global_load_lds_dwordx4 v[194:195], off
	v_lshl_add_u64 v[194:195], s[54:55], 0, v[2:3]
	s_add_i32 m0, s46, 0x2000
	s_nop 0
	global_load_lds_dwordx4 v[194:195], off
	v_lshl_add_u64 v[194:195], v[240:241], 0, s[50:51]
	s_mov_b32 m0, s28
	s_nop 0
	global_load_lds_dwordx4 v[194:195], off
	v_lshl_add_u64 v[194:195], v[242:243], 0, s[50:51]
	s_mov_b32 m0, s30
	s_nop 0
	global_load_lds_dwordx4 v[194:195], off
	s_waitcnt vmcnt(8)
	s_waitcnt lgkmcnt(0)
	s_barrier
	s_setprio 1
	s_waitcnt lgkmcnt(0)
	v_mfma_f32_16x16x32_bf16 v[62:65], v[142:145], v[178:181], v[62:65]
	v_mfma_f32_16x16x32_bf16 v[54:57], v[154:157], v[178:181], v[54:57]
	s_add_i32 s43, s43, 2
	v_mfma_f32_16x16x32_bf16 v[46:49], v[142:145], v[186:189], v[46:49]
	s_add_u32 s40, s40, 0x100
	v_mfma_f32_16x16x32_bf16 v[38:41], v[154:157], v[186:189], v[38:41]
	s_addc_u32 s42, s42, 0
	v_mfma_f32_16x16x32_bf16 v[30:33], v[142:145], v[208:211], v[30:33]
	s_add_u32 s82, s82, 0x100
	v_mfma_f32_16x16x32_bf16 v[22:25], v[154:157], v[208:211], v[22:25]
	s_addc_u32 s83, s83, 0
	v_mfma_f32_16x16x32_bf16 v[14:17], v[142:145], v[230:233], v[14:17]
	s_add_u32 s46, s82, 0xfffc0080
	v_mfma_f32_16x16x32_bf16 v[10:13], v[154:157], v[230:233], v[10:13]
	s_addc_u32 s54, s83, -1
	v_mfma_f32_16x16x32_bf16 v[62:65], v[150:153], v[182:185], v[62:65]
	s_add_i32 s55, 0, 0x10000
	v_mfma_f32_16x16x32_bf16 v[54:57], v[158:161], v[182:185], v[54:57]
	s_cmp_eq_u32 s43, 12
	v_mfma_f32_16x16x32_bf16 v[46:49], v[150:153], v[190:193], v[46:49]
	s_cselect_b32 s87, s34, s54
	v_mfma_f32_16x16x32_bf16 v[38:41], v[158:161], v[190:193], v[38:41]
	s_cselect_b32 s86, s36, s46
	v_mfma_f32_16x16x32_bf16 v[30:33], v[150:153], v[226:229], v[30:33]
	v_add_u32_e32 v149, s55, v146
	v_mfma_f32_16x16x32_bf16 v[22:25], v[158:161], v[226:229], v[22:25]
	s_cselect_b32 s85, s37, s42
	v_mfma_f32_16x16x32_bf16 v[14:17], v[150:153], v[234:237], v[14:17]
	s_cselect_b32 s84, s38, s40
	v_mfma_f32_16x16x32_bf16 v[10:13], v[158:161], v[234:237], v[10:13]
	s_add_i32 s46, 0, 0x14000
	s_setprio 0
	s_setprio 1
	v_mfma_f32_16x16x32_bf16 v[66:69], v[162:165], v[178:181], v[66:69]
	v_mfma_f32_16x16x32_bf16 v[58:61], v[170:173], v[178:181], v[58:61]
	v_mfma_f32_16x16x32_bf16 v[50:53], v[162:165], v[186:189], v[50:53]
	v_mfma_f32_16x16x32_bf16 v[42:45], v[170:173], v[186:189], v[42:45]
	v_mfma_f32_16x16x32_bf16 v[34:37], v[162:165], v[208:211], v[34:37]
	v_mfma_f32_16x16x32_bf16 v[26:29], v[170:173], v[208:211], v[26:29]
	v_mfma_f32_16x16x32_bf16 v[18:21], v[162:165], v[230:233], v[18:21]
	v_mfma_f32_16x16x32_bf16 v[6:9], v[170:173], v[230:233], v[6:9]
	v_mfma_f32_16x16x32_bf16 v[66:69], v[166:169], v[182:185], v[66:69]
	v_mfma_f32_16x16x32_bf16 v[58:61], v[174:177], v[182:185], v[58:61]
	v_mfma_f32_16x16x32_bf16 v[50:53], v[166:169], v[190:193], v[50:53]
	v_mfma_f32_16x16x32_bf16 v[42:45], v[174:177], v[190:193], v[42:45]
	v_mfma_f32_16x16x32_bf16 v[34:37], v[166:169], v[226:229], v[34:37]
	v_mfma_f32_16x16x32_bf16 v[26:29], v[174:177], v[226:229], v[26:29]
	v_mfma_f32_16x16x32_bf16 v[18:21], v[166:169], v[234:237], v[18:21]
	v_mfma_f32_16x16x32_bf16 v[6:9], v[174:177], v[234:237], v[6:9]
	s_setprio 0
	s_barrier
	s_cmp_gt_u32 s43, 13
	s_cbranch_scc0 .LBB0_188
